# w3 loads batched + gemv 16 loads in flight + PA slab rolling window
# baseline (speedup 1.0000x reference)
.LBB0_21:
	s_mov_b32 s36, 0x60000
	s_mov_b32 s37, 0
	s_mov_b32 s38, 0x6c000
	s_mov_b32 s39, 0
	s_mov_b32 s40, 0x78000
	s_mov_b32 s41, 0
	s_mov_b32 s42, 0x84000
	s_mov_b32 s43, 0
	s_mov_b32 s44, 0x90000
	s_mov_b32 s45, 0
	s_mov_b32 s46, 0x9c000
	s_mov_b32 s47, 0
	s_mov_b32 s48, 0xa8000
	s_mov_b32 s49, 0
	s_mov_b32 s50, 0xb4000
	s_mov_b32 s51, 0
	s_mul_hi_i32 s4, s22, 0x2aaaaaab
	s_lshr_b32 s5, s4, 31
	s_ashr_i32 s4, s4, 5
	s_add_i32 s23, s4, s5
	s_mul_i32 s4, s23, 0xc0
	s_sub_i32 s8, s22, s4
	s_load_dwordx2 s[4:5], s[0:1], 0x20
	s_lshl_b32 s8, s8, 6
	s_ashr_i32 s9, s8, 31
	s_mul_i32 s11, s23, 0x6000000
	s_lshl_b64 s[8:9], s[8:9], 2
	s_mul_hi_i32 s10, s23, 0x6000000
	s_waitcnt lgkmcnt(0)
	v_lshl_add_u64 v[12:13], s[4:5], 0, v[10:11]
	s_add_u32 s4, s11, s8
	s_addc_u32 s5, s10, s9
	v_lshl_add_u64 v[12:13], v[12:13], 0, s[4:5]
	s_mov_b64 s[10:11], 0
	v_mov_b32_e32 v7, v3
	v_mov_b32_e32 v9, 0
	v_mov_b32_e32 v14, 0
	v_mov_b32_e32 v15, v5
.LBB0_22:
	v_lshl_add_u64 v[16:17], v[12:13], 0, s[10:11]
	v_lshl_add_u64 v[60:61], v[16:17], 0, s[36:37]
	v_lshl_add_u64 v[62:63], v[16:17], 0, s[38:39]
	v_lshl_add_u64 v[64:65], v[16:17], 0, s[40:41]
	v_lshl_add_u64 v[66:67], v[16:17], 0, s[42:43]
	v_lshl_add_u64 v[68:69], v[16:17], 0, s[44:45]
	v_lshl_add_u64 v[70:71], v[16:17], 0, s[46:47]
	v_lshl_add_u64 v[72:73], v[16:17], 0, s[48:49]
	v_lshl_add_u64 v[74:75], v[16:17], 0, s[50:51]
	v_add_co_u32_e64 v18, s[4:5], s3, v16
	global_load_dword v40, v[16:17], off
	s_nop 0
	v_addc_co_u32_e64 v19, s[4:5], 0, v17, s[4:5]
	v_add_co_u32_e64 v20, s[4:5], s12, v16
	s_nop 1
	v_addc_co_u32_e64 v21, s[4:5], 0, v17, s[4:5]
	v_add_co_u32_e64 v22, s[4:5], s13, v16
	s_nop 1
	v_addc_co_u32_e64 v23, s[4:5], 0, v17, s[4:5]
	v_add_co_u32_e64 v24, s[4:5], s14, v16
	s_nop 1
	v_addc_co_u32_e64 v25, s[4:5], 0, v17, s[4:5]
	v_add_co_u32_e64 v26, s[4:5], s15, v16
	s_nop 1
	v_addc_co_u32_e64 v27, s[4:5], 0, v17, s[4:5]
	v_add_co_u32_e64 v28, s[4:5], s20, v16
	s_nop 1
	v_addc_co_u32_e64 v29, s[4:5], 0, v17, s[4:5]
	v_add_co_u32_e64 v16, s[4:5], s21, v16
	s_nop 1
	v_addc_co_u32_e64 v17, s[4:5], 0, v17, s[4:5]
	global_load_dword v42, v[18:19], off
	global_load_dword v44, v[20:21], off
	global_load_dword v46, v[22:23], off
	global_load_dword v48, v[24:25], off
	global_load_dword v50, v[26:27], off
	global_load_dword v52, v[28:29], off
	global_load_dword v54, v[16:17], off
	global_load_dword v60, v[60:61], off
	global_load_dword v62, v[62:63], off
	global_load_dword v64, v[64:65], off
	global_load_dword v66, v[66:67], off
	global_load_dword v68, v[68:69], off
	global_load_dword v70, v[70:71], off
	global_load_dword v72, v[72:73], off
	global_load_dword v74, v[74:75], off
	ds_read_b128 v[16:19], v7
	ds_read_b128 v[20:23], v7 offset:16
	ds_read_b128 v[24:27], v7 offset:8192
	ds_read_b128 v[28:31], v7 offset:8208
	ds_read_b128 v[32:35], v7 offset:16384
	ds_read_b128 v[36:39], v7 offset:16400
	ds_read_b128 v[80:83], v7 offset:32
	ds_read_b128 v[84:87], v7 offset:48
	ds_read_b128 v[88:91], v7 offset:8224
	ds_read_b128 v[92:95], v7 offset:8240
	ds_read_b128 v[96:99], v7 offset:16416
	ds_read_b128 v[100:103], v7 offset:16432
	s_add_u32 s10, s10, 0xc0000
	s_addc_u32 s11, s11, 0
	v_add_u32_e32 v7, 64, v7
	s_cmp_eq_u32 s10, 0xc00000
	s_waitcnt lgkmcnt(6)
	v_mov_b32_e32 v57, v24
	v_mov_b32_e32 v56, v32
	v_mov_b32_e32 v24, v33
	v_mov_b32_e32 v32, v34
	v_mov_b32_e32 v33, v26
	v_mov_b32_e32 v26, v35
	v_mov_b32_e32 v34, v36
	v_mov_b32_e32 v35, v28
	v_mov_b32_e32 v28, v37
	v_mov_b32_e32 v36, v38
	v_mov_b32_e32 v37, v30
	v_mov_b32_e32 v30, v39
	s_waitcnt vmcnt(8)
	v_fmac_f32_e32 v9, v40, v16
	v_pk_fma_f32 v[14:15], v[40:41], v[56:57], v[14:15] op_sel_hi:[0,1,1]
	v_fmac_f32_e32 v9, v42, v17
	v_pk_fma_f32 v[14:15], v[42:43], v[24:25], v[14:15] op_sel_hi:[0,1,1]
	v_fmac_f32_e32 v9, v44, v18
	v_pk_fma_f32 v[14:15], v[44:45], v[32:33], v[14:15] op_sel_hi:[0,1,1]
	v_fmac_f32_e32 v9, v46, v19
	v_pk_fma_f32 v[14:15], v[46:47], v[26:27], v[14:15] op_sel_hi:[0,1,1]
	v_fmac_f32_e32 v9, v48, v20
	v_pk_fma_f32 v[14:15], v[48:49], v[34:35], v[14:15] op_sel_hi:[0,1,1]
	v_fmac_f32_e32 v9, v50, v21
	v_pk_fma_f32 v[14:15], v[50:51], v[28:29], v[14:15] op_sel_hi:[0,1,1]
	v_fmac_f32_e32 v9, v52, v22
	v_pk_fma_f32 v[14:15], v[52:53], v[36:37], v[14:15] op_sel_hi:[0,1,1]
	v_fmac_f32_e32 v9, v54, v23
	v_pk_fma_f32 v[14:15], v[54:55], v[30:31], v[14:15] op_sel_hi:[0,1,1]
	s_waitcnt vmcnt(0) lgkmcnt(0)
	v_fmac_f32_e32 v9, v60, v80
	v_fmac_f32_e32 v15, v60, v88
	v_fmac_f32_e32 v14, v60, v96
	v_fmac_f32_e32 v9, v62, v81
	v_fmac_f32_e32 v15, v62, v89
	v_fmac_f32_e32 v14, v62, v97
	v_fmac_f32_e32 v9, v64, v82
	v_fmac_f32_e32 v15, v64, v90
	v_fmac_f32_e32 v14, v64, v98
	v_fmac_f32_e32 v9, v66, v83
	v_fmac_f32_e32 v15, v66, v91
	v_fmac_f32_e32 v14, v66, v99
	v_fmac_f32_e32 v9, v68, v84
	v_fmac_f32_e32 v15, v68, v92
	v_fmac_f32_e32 v14, v68, v100
	v_fmac_f32_e32 v9, v70, v85
	v_fmac_f32_e32 v15, v70, v93
	v_fmac_f32_e32 v14, v70, v101
	v_fmac_f32_e32 v9, v72, v86
	v_fmac_f32_e32 v15, v72, v94
	v_fmac_f32_e32 v14, v72, v102
	v_fmac_f32_e32 v9, v74, v87
	v_fmac_f32_e32 v15, v74, v95
	v_fmac_f32_e32 v14, v74, v103
	s_cbranch_scc0 .LBB0_22
	ds_write2st64_b32 v8, v9, v15 offset0:96 offset1:97
	ds_write_b32 v8, v14 offset:25088
	s_waitcnt lgkmcnt(0)
	s_barrier
	s_and_saveexec_b64 s[4:5], vcc
	s_cbranch_execz .LBB0_20
	v_add_u32_e32 v7, v6, v1
	ds_read2st64_b32 v[12:13], v7 offset0:96 offset1:99
	ds_read2st64_b32 v[14:15], v7 offset0:102 offset1:105
	ds_read2st64_b32 v[16:17], v7 offset0:108 offset1:111
	ds_read2st64_b32 v[18:19], v7 offset0:114 offset1:117
	s_load_dwordx2 s[10:11], s[0:1], 0x28
	s_mul_i32 s25, s23, 0xc000
	s_mul_hi_i32 s24, s23, 0xc000
	s_waitcnt lgkmcnt(0)
	v_add_f32_e32 v9, 0, v12
	v_add_f32_e32 v9, v9, v13
	s_add_u32 s10, s10, s25
	s_addc_u32 s11, s11, s24
	s_add_u32 s10, s10, s8
	s_addc_u32 s11, s11, s9
	v_lshl_add_u64 v[20:21], s[10:11], 0, v[4:5]
	flat_load_dword v7, v[20:21]
	v_add_f32_e32 v9, v9, v14
	v_add_f32_e32 v9, v9, v15
	v_add_f32_e32 v9, v9, v16
	v_mad_u64_u32 v[20:21], s[10:11], s23, 3, v[2:3]
	v_mov_b64_e32 v[22:23], s[6:7]
	v_add_f32_e32 v9, v9, v17
	v_mad_i64_i32 v[20:21], s[10:11], v20, s3, v[22:23]
	v_add_f32_e32 v9, v9, v18
	v_lshl_add_u64 v[20:21], v[20:21], 0, s[8:9]
	v_add_f32_e32 v9, v9, v19
	v_lshl_add_u64 v[12:13], v[20:21], 0, v[4:5]
	s_waitcnt vmcnt(0) lgkmcnt(0)
	v_add_f32_e32 v7, v9, v7
	global_store_dword v[12:13], v7, off
	s_branch .LBB0_20

.LBB0_239:
	v_add_co_u32_e32 v194, vcc, 0x50300000, v182
	s_mov_b32 s40, 0
	s_nop 0
	v_addc_co_u32_e32 v195, vcc, 0, v183, vcc
	v_add_co_u32_e32 v196, vcc, 0x50301000, v182
	s_nop 1
	v_addc_co_u32_e32 v197, vcc, 0, v183, vcc
	global_load_dwordx4 v[132:135], v[194:195], off
	global_load_dwordx4 v[136:139], v[194:195], off offset:1024
	global_load_dwordx4 v[140:143], v[194:195], off offset:2048
	global_load_dwordx4 v[144:147], v[194:195], off offset:3072
	global_load_dwordx4 v[148:151], v[196:197], off
	global_load_dwordx4 v[152:155], v[196:197], off offset:1024
	global_load_dwordx4 v[156:159], v[196:197], off offset:2048
	global_load_dwordx4 v[160:163], v[196:197], off offset:3072
.Lslab_pa_loop:
	v_add_co_u32_e32 v194, vcc, 0x400000, v194
	s_nop 1
	v_addc_co_u32_e32 v195, vcc, 0, v195, vcc
	v_add_co_u32_e32 v196, vcc, 0x400000, v196
	s_nop 1
	v_addc_co_u32_e32 v197, vcc, 0, v197, vcc
	s_add_i32 s40, s40, 1
	s_waitcnt vmcnt(7)
	v_pk_add_f32 v[124:125], v[124:125], v[132:133]
	v_pk_add_f32 v[126:127], v[126:127], v[134:135]
	global_load_dwordx4 v[132:135], v[194:195], off
	s_waitcnt vmcnt(7)
	v_pk_add_f32 v[128:129], v[128:129], v[136:137]
	v_pk_add_f32 v[130:131], v[130:131], v[138:139]
	global_load_dwordx4 v[136:139], v[194:195], off offset:1024
	s_waitcnt vmcnt(7)
	v_pk_add_f32 v[116:117], v[116:117], v[140:141]
	v_pk_add_f32 v[118:119], v[118:119], v[142:143]
	global_load_dwordx4 v[140:143], v[194:195], off offset:2048
	s_waitcnt vmcnt(7)
	v_pk_add_f32 v[120:121], v[120:121], v[144:145]
	v_pk_add_f32 v[122:123], v[122:123], v[146:147]
	global_load_dwordx4 v[144:147], v[194:195], off offset:3072
	s_waitcnt vmcnt(7)
	v_pk_add_f32 v[112:113], v[112:113], v[148:149]
	v_pk_add_f32 v[114:115], v[114:115], v[150:151]
	global_load_dwordx4 v[148:151], v[196:197], off
	s_waitcnt vmcnt(7)
	v_pk_add_f32 v[108:109], v[108:109], v[152:153]
	v_pk_add_f32 v[110:111], v[110:111], v[154:155]
	global_load_dwordx4 v[152:155], v[196:197], off offset:1024
	s_waitcnt vmcnt(7)
	v_pk_add_f32 v[104:105], v[104:105], v[156:157]
	v_pk_add_f32 v[106:107], v[106:107], v[158:159]
	global_load_dwordx4 v[156:159], v[196:197], off offset:2048
	s_waitcnt vmcnt(7)
	v_pk_add_f32 v[100:101], v[100:101], v[160:161]
	v_pk_add_f32 v[102:103], v[102:103], v[162:163]
	global_load_dwordx4 v[160:163], v[196:197], off offset:3072
	s_cmp_lt_u32 s40, 10
	s_cbranch_scc1 .Lslab_pa_loop
	s_waitcnt vmcnt(7)
	v_pk_add_f32 v[124:125], v[124:125], v[132:133]
	v_pk_add_f32 v[126:127], v[126:127], v[134:135]
	s_waitcnt vmcnt(6)
	v_pk_add_f32 v[128:129], v[128:129], v[136:137]
	v_pk_add_f32 v[130:131], v[130:131], v[138:139]
	s_waitcnt vmcnt(5)
	v_pk_add_f32 v[116:117], v[116:117], v[140:141]
	v_pk_add_f32 v[118:119], v[118:119], v[142:143]
	s_waitcnt vmcnt(4)
	v_pk_add_f32 v[120:121], v[120:121], v[144:145]
	v_pk_add_f32 v[122:123], v[122:123], v[146:147]
	s_waitcnt vmcnt(3)
	v_pk_add_f32 v[112:113], v[112:113], v[148:149]
	v_pk_add_f32 v[114:115], v[114:115], v[150:151]
	s_waitcnt vmcnt(2)
	v_pk_add_f32 v[108:109], v[108:109], v[152:153]
	v_pk_add_f32 v[110:111], v[110:111], v[154:155]
	s_waitcnt vmcnt(1)
	v_pk_add_f32 v[104:105], v[104:105], v[156:157]
	v_pk_add_f32 v[106:107], v[106:107], v[158:159]
	s_waitcnt vmcnt(0)
	v_pk_add_f32 v[100:101], v[100:101], v[160:161]
	v_pk_add_f32 v[102:103], v[102:103], v[162:163]
	v_mov_b64_e32 v[152:153], v[124:125]
	v_mov_b64_e32 v[154:155], v[126:127]
	v_mov_b64_e32 v[156:157], v[128:129]
	v_mov_b64_e32 v[158:159], v[130:131]
	v_mov_b64_e32 v[148:149], v[116:117]
	v_mov_b64_e32 v[150:151], v[118:119]
	v_mov_b64_e32 v[144:145], v[120:121]
	v_mov_b64_e32 v[146:147], v[122:123]
	v_mov_b64_e32 v[140:141], v[112:113]
	v_mov_b64_e32 v[142:143], v[114:115]
	v_mov_b64_e32 v[136:137], v[108:109]
	v_mov_b64_e32 v[138:139], v[110:111]
	v_mov_b64_e32 v[132:133], v[104:105]
	v_mov_b64_e32 v[134:135], v[106:107]
	v_mov_b64_e32 v[160:161], v[100:101]
	v_mov_b64_e32 v[162:163], v[102:103]
	s_mov_b32 s40, 0x2000000
	s_mov_b32 s41, 0
	s_mov_b64 s[38:39], -1
	s_branch .LBB0_229

.LBB0_539:
	s_or_b64 exec, exec, s[16:17]
	s_waitcnt lgkmcnt(0)
	s_barrier
	s_load_dwordx2 s[10:11], s[0:1], 0xd8
	v_and_b32_e32 v2, 0x200, v2
	v_or_b32_e32 v2, s9, v2
	v_bfe_u32 v12, v72, 4, 2
	v_and_b32_e32 v78, 15, v72
	s_waitcnt lgkmcnt(0)
	s_add_u32 s10, s10, s36
	v_or3_b32 v2, v2, v6, v7
	s_addc_u32 s11, s11, s37
	v_lshl_add_u64 v[4:5], v[2:3], 2, s[10:11]
	v_cmp_gt_u32_e64 s[40:41], 4, v78
	v_mov_b32_e32 v9, 0
	v_lshlrev_b32_e32 v2, 16, v12
	v_mov_b32_e32 v8, 0
	v_mov_b32_e32 v8, 0
	v_mov_b32_e32 v9, 0
	v_mov_b32_e32 v13, 0
	v_mov_b32_e32 v10, 0
	v_mov_b32_e32 v14, 0
	v_mov_b32_e32 v11, 0
	v_mov_b32_e32 v15, 0
	v_mov_b32_e32 v16, 0
	v_mov_b32_e32 v17, 0
	v_mov_b32_e32 v18, 0
	v_mov_b32_e32 v19, 0
	v_mov_b32_e32 v20, 0
	v_mov_b32_e32 v21, 0
	v_mov_b32_e32 v22, 0
	v_mov_b32_e32 v23, 0
	v_mov_b32_e32 v24, 0
	s_and_saveexec_b64 s[14:15], s[40:41]
	s_cbranch_execz .Lw3_skip_1
	v_lshl_add_u64 v[4:5], v[4:5], 0, v[2:3]
	global_load_dword v8, v[4:5], off
	v_add_co_u32_e32 v26, vcc, 0x40000, v4
	s_nop 1
	v_addc_co_u32_e32 v27, vcc, 0, v5, vcc
	global_load_dword v9, v[26:27], off
	v_add_co_u32_e32 v26, vcc, 0x2000, v4
	s_nop 1
	v_addc_co_u32_e32 v27, vcc, 0, v5, vcc
	global_load_dword v13, v[26:27], off
	v_add_co_u32_e32 v26, vcc, 0x42000, v4
	s_nop 1
	v_addc_co_u32_e32 v27, vcc, 0, v5, vcc
	global_load_dword v10, v[26:27], off
	v_add_co_u32_e32 v26, vcc, 0x4000, v4
	s_nop 1
	v_addc_co_u32_e32 v27, vcc, 0, v5, vcc
	global_load_dword v14, v[26:27], off
	v_add_co_u32_e32 v26, vcc, 0x44000, v4
	s_nop 1
	v_addc_co_u32_e32 v27, vcc, 0, v5, vcc
	global_load_dword v11, v[26:27], off
	v_add_co_u32_e32 v26, vcc, 0x6000, v4
	s_nop 1
	v_addc_co_u32_e32 v27, vcc, 0, v5, vcc
	global_load_dword v15, v[26:27], off
	v_add_co_u32_e32 v26, vcc, 0x46000, v4
	s_nop 1
	v_addc_co_u32_e32 v27, vcc, 0, v5, vcc
	global_load_dword v16, v[26:27], off
	v_add_co_u32_e32 v26, vcc, 0x8000, v4
	s_nop 1
	v_addc_co_u32_e32 v27, vcc, 0, v5, vcc
	global_load_dword v17, v[26:27], off
	v_add_co_u32_e32 v26, vcc, 0x48000, v4
	s_nop 1
	v_addc_co_u32_e32 v27, vcc, 0, v5, vcc
	global_load_dword v18, v[26:27], off
	v_add_co_u32_e32 v26, vcc, 0xa000, v4
	s_nop 1
	v_addc_co_u32_e32 v27, vcc, 0, v5, vcc
	global_load_dword v19, v[26:27], off
	v_add_co_u32_e32 v26, vcc, 0x4a000, v4
	s_nop 1
	v_addc_co_u32_e32 v27, vcc, 0, v5, vcc
	global_load_dword v20, v[26:27], off
	v_add_co_u32_e32 v26, vcc, 0xc000, v4
	s_nop 1
	v_addc_co_u32_e32 v27, vcc, 0, v5, vcc
	global_load_dword v21, v[26:27], off
	v_add_co_u32_e32 v26, vcc, 0x4c000, v4
	s_nop 1
	v_addc_co_u32_e32 v27, vcc, 0, v5, vcc
	global_load_dword v22, v[26:27], off
	v_add_co_u32_e32 v26, vcc, 0xe000, v4
	s_nop 1
	v_addc_co_u32_e32 v27, vcc, 0, v5, vcc
	global_load_dword v23, v[26:27], off
	v_add_co_u32_e32 v26, vcc, 0x4e000, v4
	s_nop 1
	v_addc_co_u32_e32 v27, vcc, 0, v5, vcc
	global_load_dword v24, v[26:27], off
	s_waitcnt vmcnt(0)
	v_cvt_f16_f32_e32 v8, v8
	v_cvt_f16_f32_e32 v9, v9
	v_cvt_f16_f32_e32 v13, v13
	v_cvt_f16_f32_e32 v10, v10
	v_cvt_f16_f32_e32 v14, v14
	v_cvt_f16_f32_e32 v11, v11
	v_cvt_f16_f32_e32 v15, v15
	v_cvt_f16_f32_e32 v16, v16
	v_cvt_f16_f32_e32 v17, v17
	v_cvt_f16_f32_e32 v18, v18
	v_cvt_f16_f32_e32 v19, v19
	v_cvt_f16_f32_e32 v20, v20
	v_cvt_f16_f32_e32 v21, v21
	v_cvt_f16_f32_e32 v22, v22
	v_cvt_f16_f32_e32 v23, v23
	v_cvt_f16_f32_e32 v24, v24

.LBB0_905:
	s_or_b64 exec, exec, s[16:17]
	s_waitcnt lgkmcnt(0)
	s_barrier
	s_load_dwordx2 s[14:15], s[0:1], 0xd8
	v_and_b32_e32 v2, 0x200, v2
	v_or_b32_e32 v2, s11, v2
	v_bfe_u32 v12, v72, 4, 2
	v_and_b32_e32 v78, 15, v72
	s_waitcnt lgkmcnt(0)
	s_add_u32 s14, s14, s48
	v_or3_b32 v2, v2, v6, v7
	s_addc_u32 s15, s15, s49
	v_lshl_add_u64 v[4:5], v[2:3], 2, s[14:15]
	v_cmp_gt_u32_e64 s[40:41], 4, v78
	v_mov_b32_e32 v9, 0
	v_lshlrev_b32_e32 v2, 16, v12
	v_mov_b32_e32 v8, 0
	v_mov_b32_e32 v8, 0
	v_mov_b32_e32 v9, 0
	v_mov_b32_e32 v13, 0
	v_mov_b32_e32 v10, 0
	v_mov_b32_e32 v14, 0
	v_mov_b32_e32 v11, 0
	v_mov_b32_e32 v15, 0
	v_mov_b32_e32 v16, 0
	v_mov_b32_e32 v17, 0
	v_mov_b32_e32 v18, 0
	v_mov_b32_e32 v19, 0
	v_mov_b32_e32 v20, 0
	v_mov_b32_e32 v21, 0
	v_mov_b32_e32 v22, 0
	v_mov_b32_e32 v23, 0
	v_mov_b32_e32 v24, 0
	s_and_saveexec_b64 s[14:15], s[40:41]
	s_cbranch_execz .Lw3_skip_2
	v_lshl_add_u64 v[4:5], v[4:5], 0, v[2:3]
	global_load_dword v8, v[4:5], off
	v_add_co_u32_e32 v26, vcc, 0x40000, v4
	s_nop 1
	v_addc_co_u32_e32 v27, vcc, 0, v5, vcc
	global_load_dword v9, v[26:27], off
	v_add_co_u32_e32 v26, vcc, 0x2000, v4
	s_nop 1
	v_addc_co_u32_e32 v27, vcc, 0, v5, vcc
	global_load_dword v13, v[26:27], off
	v_add_co_u32_e32 v26, vcc, 0x42000, v4
	s_nop 1
	v_addc_co_u32_e32 v27, vcc, 0, v5, vcc
	global_load_dword v10, v[26:27], off
	v_add_co_u32_e32 v26, vcc, 0x4000, v4
	s_nop 1
	v_addc_co_u32_e32 v27, vcc, 0, v5, vcc
	global_load_dword v14, v[26:27], off
	v_add_co_u32_e32 v26, vcc, 0x44000, v4
	s_nop 1
	v_addc_co_u32_e32 v27, vcc, 0, v5, vcc
	global_load_dword v11, v[26:27], off
	v_add_co_u32_e32 v26, vcc, 0x6000, v4
	s_nop 1
	v_addc_co_u32_e32 v27, vcc, 0, v5, vcc
	global_load_dword v15, v[26:27], off
	v_add_co_u32_e32 v26, vcc, 0x46000, v4
	s_nop 1
	v_addc_co_u32_e32 v27, vcc, 0, v5, vcc
	global_load_dword v16, v[26:27], off
	v_add_co_u32_e32 v26, vcc, 0x8000, v4
	s_nop 1
	v_addc_co_u32_e32 v27, vcc, 0, v5, vcc
	global_load_dword v17, v[26:27], off
	v_add_co_u32_e32 v26, vcc, 0x48000, v4
	s_nop 1
	v_addc_co_u32_e32 v27, vcc, 0, v5, vcc
	global_load_dword v18, v[26:27], off
	v_add_co_u32_e32 v26, vcc, 0xa000, v4
	s_nop 1
	v_addc_co_u32_e32 v27, vcc, 0, v5, vcc
	global_load_dword v19, v[26:27], off
	v_add_co_u32_e32 v26, vcc, 0x4a000, v4
	s_nop 1
	v_addc_co_u32_e32 v27, vcc, 0, v5, vcc
	global_load_dword v20, v[26:27], off
	v_add_co_u32_e32 v26, vcc, 0xc000, v4
	s_nop 1
	v_addc_co_u32_e32 v27, vcc, 0, v5, vcc
	global_load_dword v21, v[26:27], off
	v_add_co_u32_e32 v26, vcc, 0x4c000, v4
	s_nop 1
	v_addc_co_u32_e32 v27, vcc, 0, v5, vcc
	global_load_dword v22, v[26:27], off
	v_add_co_u32_e32 v26, vcc, 0xe000, v4
	s_nop 1
	v_addc_co_u32_e32 v27, vcc, 0, v5, vcc
	global_load_dword v23, v[26:27], off
	v_add_co_u32_e32 v26, vcc, 0x4e000, v4
	s_nop 1
	v_addc_co_u32_e32 v27, vcc, 0, v5, vcc
	global_load_dword v24, v[26:27], off
	s_waitcnt vmcnt(0)
	v_cvt_f16_f32_e32 v8, v8
	v_cvt_f16_f32_e32 v9, v9
	v_cvt_f16_f32_e32 v13, v13
	v_cvt_f16_f32_e32 v10, v10
	v_cvt_f16_f32_e32 v14, v14
	v_cvt_f16_f32_e32 v11, v11
	v_cvt_f16_f32_e32 v15, v15
	v_cvt_f16_f32_e32 v16, v16
	v_cvt_f16_f32_e32 v17, v17
	v_cvt_f16_f32_e32 v18, v18
	v_cvt_f16_f32_e32 v19, v19
	v_cvt_f16_f32_e32 v20, v20
	v_cvt_f16_f32_e32 v21, v21
	v_cvt_f16_f32_e32 v22, v22
	v_cvt_f16_f32_e32 v23, v23
	v_cvt_f16_f32_e32 v24, v24

.LBB0_1765:
	s_or_b64 exec, exec, s[16:17]
	s_waitcnt lgkmcnt(0)
	s_barrier
	s_load_dwordx2 s[12:13], s[0:1], 0xd8
	v_and_b32_e32 v2, 0x200, v2
	v_or_b32_e32 v2, s10, v2
	v_bfe_u32 v12, v72, 4, 2
	v_and_b32_e32 v78, 15, v72
	s_waitcnt lgkmcnt(0)
	s_add_u32 s10, s12, s36
	v_or3_b32 v2, v2, v6, v7
	s_addc_u32 s11, s13, s37
	v_lshl_add_u64 v[4:5], v[2:3], 2, s[10:11]
	v_cmp_gt_u32_e64 s[40:41], 4, v78
	v_mov_b32_e32 v9, 0
	v_lshlrev_b32_e32 v2, 16, v12
	v_mov_b32_e32 v8, 0
	v_mov_b32_e32 v8, 0
	v_mov_b32_e32 v9, 0
	v_mov_b32_e32 v13, 0
	v_mov_b32_e32 v10, 0
	v_mov_b32_e32 v14, 0
	v_mov_b32_e32 v11, 0
	v_mov_b32_e32 v15, 0
	v_mov_b32_e32 v16, 0
	v_mov_b32_e32 v17, 0
	v_mov_b32_e32 v18, 0
	v_mov_b32_e32 v19, 0
	v_mov_b32_e32 v20, 0
	v_mov_b32_e32 v21, 0
	v_mov_b32_e32 v22, 0
	v_mov_b32_e32 v23, 0
	v_mov_b32_e32 v24, 0
	s_and_saveexec_b64 s[14:15], s[40:41]
	s_cbranch_execz .Lw3_skip_3
	v_lshl_add_u64 v[4:5], v[4:5], 0, v[2:3]
	global_load_dword v8, v[4:5], off
	v_add_co_u32_e32 v26, vcc, 0x40000, v4
	s_nop 1
	v_addc_co_u32_e32 v27, vcc, 0, v5, vcc
	global_load_dword v9, v[26:27], off
	v_add_co_u32_e32 v26, vcc, 0x2000, v4
	s_nop 1
	v_addc_co_u32_e32 v27, vcc, 0, v5, vcc
	global_load_dword v13, v[26:27], off
	v_add_co_u32_e32 v26, vcc, 0x42000, v4
	s_nop 1
	v_addc_co_u32_e32 v27, vcc, 0, v5, vcc
	global_load_dword v10, v[26:27], off
	v_add_co_u32_e32 v26, vcc, 0x4000, v4
	s_nop 1
	v_addc_co_u32_e32 v27, vcc, 0, v5, vcc
	global_load_dword v14, v[26:27], off
	v_add_co_u32_e32 v26, vcc, 0x44000, v4
	s_nop 1
	v_addc_co_u32_e32 v27, vcc, 0, v5, vcc
	global_load_dword v11, v[26:27], off
	v_add_co_u32_e32 v26, vcc, 0x6000, v4
	s_nop 1
	v_addc_co_u32_e32 v27, vcc, 0, v5, vcc
	global_load_dword v15, v[26:27], off
	v_add_co_u32_e32 v26, vcc, 0x46000, v4
	s_nop 1
	v_addc_co_u32_e32 v27, vcc, 0, v5, vcc
	global_load_dword v16, v[26:27], off
	v_add_co_u32_e32 v26, vcc, 0x8000, v4
	s_nop 1
	v_addc_co_u32_e32 v27, vcc, 0, v5, vcc
	global_load_dword v17, v[26:27], off
	v_add_co_u32_e32 v26, vcc, 0x48000, v4
	s_nop 1
	v_addc_co_u32_e32 v27, vcc, 0, v5, vcc
	global_load_dword v18, v[26:27], off
	v_add_co_u32_e32 v26, vcc, 0xa000, v4
	s_nop 1
	v_addc_co_u32_e32 v27, vcc, 0, v5, vcc
	global_load_dword v19, v[26:27], off
	v_add_co_u32_e32 v26, vcc, 0x4a000, v4
	s_nop 1
	v_addc_co_u32_e32 v27, vcc, 0, v5, vcc
	global_load_dword v20, v[26:27], off
	v_add_co_u32_e32 v26, vcc, 0xc000, v4
	s_nop 1
	v_addc_co_u32_e32 v27, vcc, 0, v5, vcc
	global_load_dword v21, v[26:27], off
	v_add_co_u32_e32 v26, vcc, 0x4c000, v4
	s_nop 1
	v_addc_co_u32_e32 v27, vcc, 0, v5, vcc
	global_load_dword v22, v[26:27], off
	v_add_co_u32_e32 v26, vcc, 0xe000, v4
	s_nop 1
	v_addc_co_u32_e32 v27, vcc, 0, v5, vcc
	global_load_dword v23, v[26:27], off
	v_add_co_u32_e32 v26, vcc, 0x4e000, v4
	s_nop 1
	v_addc_co_u32_e32 v27, vcc, 0, v5, vcc
	global_load_dword v24, v[26:27], off
	s_waitcnt vmcnt(0)
	v_cvt_f16_f32_e32 v8, v8
	v_cvt_f16_f32_e32 v9, v9
	v_cvt_f16_f32_e32 v13, v13
	v_cvt_f16_f32_e32 v10, v10
	v_cvt_f16_f32_e32 v14, v14
	v_cvt_f16_f32_e32 v11, v11
	v_cvt_f16_f32_e32 v15, v15
	v_cvt_f16_f32_e32 v16, v16
	v_cvt_f16_f32_e32 v17, v17
	v_cvt_f16_f32_e32 v18, v18
	v_cvt_f16_f32_e32 v19, v19
	v_cvt_f16_f32_e32 v20, v20
	v_cvt_f16_f32_e32 v21, v21
	v_cvt_f16_f32_e32 v22, v22
	v_cvt_f16_f32_e32 v23, v23
	v_cvt_f16_f32_e32 v24, v24
